# diff attention units without the static s_setprio 1 on waves 0-3 (timing only)
# baseline (speedup 1.0000x reference)
.LBB0_529:
	s_and_b64 vcc, exec, s[4:5]
	s_cbranch_vccz .LBB0_589
	s_mov_b32 s0, s97
	v_mbcnt_lo_u32_b32 v1, -1, 0
	v_mbcnt_hi_u32_b32 v1, -1, v1
	s_nop 0
	v_lshl_or_b32 v0, s0, 6, v1
	s_nop 0
	v_readfirstlane_b32 s0, v0
	s_ashr_i32 s6, s0, 6
	s_cmp_lt_i32 s6, 4
	s_cselect_b64 s[14:15], -1, 0
	s_cmp_gt_i32 s6, 3
	s_cselect_b64 s[4:5], -1, 0
	s_and_b64 vcc, exec, s[4:5]
	s_cbranch_vccnz .LBB0_532
	s_nop 0
